# speedup vs baseline: 1.0084x; 1.0084x over previous
; template <int MODE> ...
;     ...
;       const bool active = (k32 <= w_last) && (w_first < L);
;       SPHASE(sub, active);
.LBB0_350:
	s_sub_i32 s8, s14, 31
	v_cmp_le_i32_e32 vcc, s8, v167
	s_and_b64 s[10:11], s[6:7], vcc
	s_and_saveexec_b64 s[8:9], s[10:11]
	s_cbranch_execz .LBB0_352
	ds_read_b128 v[2:5], v204 offset:512
	ds_read_b128 v[190:193], v205 offset:512
	ds_read_b128 v[222:225], v206 offset:512
	ds_read_b128 v[226:229], v207 offset:512
	ds_read_b128 v[230:233], v208 offset:512
	ds_read_b128 v[234:237], v209 offset:512
	ds_read_b128 v[238:241], v210 offset:512
	ds_read_b128 v[242:245], v211 offset:512
	ds_read_b128 v[246:249], v212 offset:512
	s_waitcnt vmcnt(16) lgkmcnt(8)
	v_mfma_f32_32x32x16_bf16 v[2:17], v[2:5], v[18:21], 0
	s_waitcnt vmcnt(15) lgkmcnt(7)
	v_mfma_f32_32x32x16_bf16 v[2:17], v[190:193], v[22:25], v[2:17]
	ds_read_b128 v[190:193], v213 offset:512
	s_waitcnt vmcnt(14) lgkmcnt(7)
	v_mfma_f32_32x32x16_bf16 v[2:17], v[222:225], v[26:29], v[2:17]
	ds_read_b128 v[222:225], v214 offset:512
	s_waitcnt vmcnt(13) lgkmcnt(7)
	v_mfma_f32_32x32x16_bf16 v[2:17], v[226:229], v[96:99], v[2:17]
	ds_read_b128 v[226:229], v215 offset:512
	s_waitcnt vmcnt(12) lgkmcnt(7)
	v_mfma_f32_32x32x16_bf16 v[2:17], v[230:233], v[100:103], v[2:17]
	s_waitcnt vmcnt(11) lgkmcnt(6)
	v_mfma_f32_32x32x16_bf16 v[2:17], v[234:237], v[104:107], v[2:17]
	s_waitcnt vmcnt(10) lgkmcnt(5)
	v_mfma_f32_32x32x16_bf16 v[2:17], v[238:241], v[108:111], v[2:17]
	s_waitcnt vmcnt(9) lgkmcnt(4)
	v_mfma_f32_32x32x16_bf16 v[2:17], v[242:245], v[112:115], v[2:17]
	s_waitcnt vmcnt(8) lgkmcnt(3)
	v_mfma_f32_32x32x16_bf16 v[2:17], v[246:249], v[116:119], v[2:17]
	s_waitcnt vmcnt(7) lgkmcnt(2)
	v_mfma_f32_32x32x16_bf16 v[2:17], v[190:193], v[120:123], v[2:17]
	s_waitcnt vmcnt(6) lgkmcnt(1)
	v_mfma_f32_32x32x16_bf16 v[2:17], v[222:225], v[124:127], v[2:17]
	s_waitcnt vmcnt(5) lgkmcnt(0)
	v_mfma_f32_32x32x16_bf16 v[2:17], v[226:229], v[128:131], v[2:17]

; template <int MODE> ...
;     ...
;     __syncthreads();
;     vcur ^= 1;
.LBB0_364:
	v_xor_b32_e32 v31, 0x10000, v31
	v_xor_b32_e32 v204, 0x10000, v204
	v_xor_b32_e32 v205, 0x10000, v205
	v_xor_b32_e32 v206, 0x10000, v206
	v_xor_b32_e32 v207, 0x10000, v207
	v_xor_b32_e32 v208, 0x10000, v208
	v_xor_b32_e32 v209, 0x10000, v209
	v_xor_b32_e32 v210, 0x10000, v210
	v_xor_b32_e32 v211, 0x10000, v211
	v_xor_b32_e32 v212, 0x10000, v212
	v_xor_b32_e32 v213, 0x10000, v213
	v_xor_b32_e32 v214, 0x10000, v214
	v_xor_b32_e32 v215, 0x10000, v215
	s_cmp_lt_u32 s13, 2
	s_cbranch_scc1 .LBB0_366
	s_add_i32 s74, s14, 0xffffff41
	s_lshl_b64 s[8:9], s[74:75], 11
	s_waitcnt vmcnt(3)
	v_lshl_add_u64 v[136:137], v[156:157], 0, s[8:9]
	s_lshl_b64 s[8:9], s[74:75], 7
	s_waitcnt vmcnt(2)
	v_lshl_add_u64 v[140:141], v[158:159], 0, s[8:9]
	s_lshl_b64 s[8:9], s[74:75], 1
	s_waitcnt vmcnt(1)
	v_lshl_add_u64 v[144:145], v[160:161], 0, s[8:9]
	s_waitcnt vmcnt(0)
	v_lshl_add_u64 v[148:149], v[162:163], 0, s[8:9]
	global_load_dwordx4 v[132:135], v[136:137], off
	s_nop 0
	global_load_dwordx4 v[136:139], v[136:137], off offset:128
	s_nop 0
	global_load_dwordx4 v[140:143], v[140:141], off
	s_nop 0
	global_load_dwordx4 v[144:147], v[144:145], off
	s_nop 0
	global_load_dwordx4 v[148:151], v[148:149], off
